# strategy 5 direct HBM->LDS loads, second variant: gemm_f32 LDS-DMA issued right after the iteration barrier (full-iteration latency budget), skipped in the last two trips
# speedup vs baseline: 1.0073x; 1.0020x over previous
; #define ZERO_ACC8(acc, NJ_)                             \
;   _Pragma("unroll") for (int i_ = 0; i_ < 8; ++i_)      \
;   _Pragma("unroll") for (int j_ = 0; j_ < (NJ_); ++j_) { acc[i_][j_] = (f32x4){0.f, 0.f, 0.f, 0.f}; }
; template <int MI, int NJ> ...
;     ...
;   if (!pre) G8LOADP(Ag, Bg);
;   G8STORE(0);
;   {
;     const u16* ga_ = (1 < nk) ? Ag + 64 : Ag + nAoff;
;     const u16* gb_ = (1 < nk) ? Bg + 64 : Bg + nBoff;
;     G8LOADP(ga_, gb_);
;   }
;   __syncthreads();
;   const int sw0 = ((lane >> 4) ^ (lane & 7)) * 8;
;   const int dsw = (sw0 ^ 32) - sw0;
;   const u16* ra_ = sA + (wm * (16 * MI) + (lane & 15)) * 64 + sw0;
;   const u16* rb_ = sB + (wn * (16 * NJ) + (lane & 15)) * 64 + sw0;
;   for (int kt = 0; kt < nk; ++kt) {
;     const int buf = kt & 1;
;     {
;       G8STORE(buf ^ 1);
;       const u16* ga_ = (kt + 2 < nk) ? Ag + (kt + 2) * 64 : Ag + nAoff;
;       const u16* gb_ = (kt + 2 < nk) ? Bg + (kt + 2) * 64 : Bg + nBoff;
;       G8LOADP(ga_, gb_);
;     }
; __device__ __forceinline__ void phase_gemm_f32(const u16* A, const u16* Bt, int K, u16* out, u16* smem,
;                                                volatile LAS unsigned* vb_) {
;     ...
;   for (int lt = vb >> 3; lt < 8 * 4; lt += step) {
;     const int nt = lt >> 3, mt = (vb & 7) * 8 + (lt & 7);
;     const int ltn = (lt + step < 8 * 4) ? lt + step : lt;
;     f32x4 acc[8][4];
;     ZERO_ACC8(acc, 4);
;     gemm8<8, 4>(acc, G8REGS_ARGS, pre, A, K, Bt, K, 0, K, mt * 256, nt * 256, ((vb & 7) * 8 + (ltn & 7)) * 256, (ltn >> 3) * 256, 0, smem, tid);
.Lk1done_gf32:
	s_add_i32 s36, s37, s70
	s_cmp_gt_i32 s36, 31
	s_cselect_b64 s[40:41], -1, 0
	s_cmp_lt_i32 s36, 32
	s_cselect_b32 s12, s36, s37
	s_and_b32 s13, s12, 7
	s_lshl_b32 s12, s12, 5
	s_and_b32 s37, s12, 0xffffff00
	s_sub_i32 s12, s13, s38
	s_lshl_b32 s13, s12, 8
	s_sub_i32 s38, s37, s42
	v_mov_b32_e32 v22, 0
	s_mul_hi_i32 s12, s13, s10
	s_mul_i32 s13, s13, s10
	s_mul_hi_i32 s37, s38, s10
	s_mul_i32 s38, s38, s10
	s_movk_i32 s39, 0x80
	s_mov_b32 s43, 0
	s_mov_b32 s44, 0
	v_mov_b32_e32 v23, v22
	v_mov_b32_e32 v24, v22
	v_mov_b32_e32 v25, v22
	v_mov_b32_e32 v26, v22
	v_mov_b32_e32 v27, v22
	v_mov_b32_e32 v28, v22
	v_mov_b32_e32 v29, v22
	v_mov_b32_e32 v30, v22
	v_mov_b32_e32 v31, v22
	v_mov_b32_e32 v32, v22
	v_mov_b32_e32 v33, v22
	v_mov_b32_e32 v34, v22
	v_mov_b32_e32 v35, v22
	v_mov_b32_e32 v36, v22
	v_mov_b32_e32 v37, v22
	v_mov_b32_e32 v38, v22
	v_mov_b32_e32 v39, v22
	v_mov_b32_e32 v40, v22
	v_mov_b32_e32 v41, v22
	v_mov_b32_e32 v46, v22
	v_mov_b32_e32 v47, v22
	v_mov_b32_e32 v48, v22
	v_mov_b32_e32 v49, v22
	v_mov_b32_e32 v50, v22
	v_mov_b32_e32 v51, v22
	v_mov_b32_e32 v52, v22
	v_mov_b32_e32 v53, v22
	v_mov_b32_e32 v54, v22
	v_mov_b32_e32 v55, v22
	v_mov_b32_e32 v56, v22
	v_mov_b32_e32 v57, v22
	v_mov_b32_e32 v58, v22
	v_mov_b32_e32 v59, v22
	v_mov_b32_e32 v60, v22
	v_mov_b32_e32 v61, v22
	v_mov_b32_e32 v66, v22
	v_mov_b32_e32 v67, v22
	v_mov_b32_e32 v68, v22
	v_mov_b32_e32 v69, v22
	v_mov_b32_e32 v70, v22
	v_mov_b32_e32 v71, v22
	v_mov_b32_e32 v72, v22
	v_mov_b32_e32 v73, v22
	v_mov_b32_e32 v78, v22
	v_mov_b32_e32 v79, v22
	v_mov_b32_e32 v80, v22
	v_mov_b32_e32 v81, v22
	v_mov_b32_e32 v82, v22
	v_mov_b32_e32 v83, v22
	v_mov_b32_e32 v84, v22
	v_mov_b32_e32 v85, v22
	v_mov_b32_e32 v86, v22
	v_mov_b32_e32 v87, v22
	v_mov_b32_e32 v88, v22
	v_mov_b32_e32 v89, v22
	v_mov_b32_e32 v90, v22
	v_mov_b32_e32 v91, v22
	v_mov_b32_e32 v92, v22
	v_mov_b32_e32 v93, v22
	v_mov_b32_e32 v94, v22
	v_mov_b32_e32 v95, v22
	v_mov_b32_e32 v96, v22
	v_mov_b32_e32 v97, v22
	v_mov_b32_e32 v98, v22
	v_mov_b32_e32 v99, v22
	v_mov_b32_e32 v100, v22
	v_mov_b32_e32 v101, v22
	v_mov_b32_e32 v102, v22
	v_mov_b32_e32 v103, v22
	v_mov_b32_e32 v104, v22
	v_mov_b32_e32 v105, v22
	v_mov_b32_e32 v106, v22
	v_mov_b32_e32 v107, v22
	v_mov_b32_e32 v108, v22
	v_mov_b32_e32 v109, v22
	v_mov_b32_e32 v110, v22
	v_mov_b32_e32 v111, v22
	v_mov_b32_e32 v112, v22
	v_mov_b32_e32 v113, v22
	v_mov_b32_e32 v114, v22
	v_mov_b32_e32 v115, v22
	v_mov_b32_e32 v116, v22
	v_mov_b32_e32 v117, v22
	v_mov_b32_e32 v118, v22
	v_mov_b32_e32 v119, v22
	v_mov_b32_e32 v120, v22
	v_mov_b32_e32 v121, v22
	v_mov_b32_e32 v122, v22
	v_mov_b32_e32 v123, v22
	v_mov_b32_e32 v124, v22
	v_mov_b32_e32 v125, v22
	v_mov_b32_e32 v126, v22
	v_mov_b32_e32 v127, v22
	v_mov_b32_e32 v128, v22
	v_mov_b32_e32 v129, v22
	v_mov_b32_e32 v130, v22
	v_mov_b32_e32 v131, v22
	v_mov_b32_e32 v132, v22
	v_mov_b32_e32 v133, v22
	v_mov_b32_e32 v134, v22
	v_mov_b32_e32 v135, v22
	v_mov_b32_e32 v136, v22
	v_mov_b32_e32 v137, v22
	v_mov_b32_e32 v138, v22
	v_mov_b32_e32 v139, v22
	v_mov_b32_e32 v140, v22
	v_mov_b32_e32 v141, v22
	v_mov_b32_e32 v142, v22
	v_mov_b32_e32 v143, v22
	v_mov_b32_e32 v144, v22
	v_mov_b32_e32 v145, v22
	v_mov_b32_e32 v146, v22
	v_mov_b32_e32 v147, v22
	v_mov_b32_e32 v148, v22
	v_mov_b32_e32 v149, v22
	v_mov_b32_e32 v150, v22
	v_mov_b32_e32 v151, v22
	v_mov_b32_e32 v152, v22
	v_mov_b32_e32 v153, v22
	v_mov_b32_e32 v154, v22
	v_mov_b32_e32 v155, v22
	v_mov_b32_e32 v156, v22
	v_mov_b32_e32 v157, v22
	v_mov_b32_e32 v158, v22
	v_mov_b32_e32 v159, v22
	v_mov_b32_e32 v160, v22
	v_mov_b32_e32 v161, v22
	s_waitcnt lgkmcnt(0)
	s_barrier
	s_and_b32 s45, s43, 0x4000
	s_sub_i32 s67, s39, 64
	s_add_i32 s46, s44, 1
	s_cmp_lt_u32 s46, s21
	s_cselect_b32 s47, 0, s12
	s_cselect_b32 s46, s67, s13
	s_cselect_b32 s49, 0, s37
	s_cselect_b32 s48, s67, s38
	s_lshl_b64 s[46:47], s[46:47], 1
	s_lshl_b64 s[48:49], s[48:49], 1
	s_add_u32 s50, s62, s46
	s_addc_u32 s51, s63, s47
	s_add_u32 s52, s64, s48
	s_addc_u32 s53, s65, s49
	s_lshl_b32 s45, s45, 1
	v_add_u32_e32 v0, s45, v187
	v_add_u32_e32 v191, s45, v188
	s_add_i32 s98, s44, 1
	s_cmp_lt_u32 s98, s21
	s_cbranch_scc0 .Ldma_skip_p
	s_and_b32 s99, s44, 1
	s_xor_b32 s99, s99, 1
	s_lshl_b32 s99, s99, 15
	s_add_u32 s99, s99, s66
	s_mov_b32 m0, s99
	s_nop 0
	global_load_lds_dwordx4 v234, s[50:51]
	s_add_u32 m0, s99, 0x2000
	s_nop 0
	global_load_lds_dwordx4 v235, s[50:51]
	s_add_u32 m0, s99, 0x4000
	s_nop 0
	global_load_lds_dwordx4 v236, s[50:51]
	s_add_u32 m0, s99, 0x6000
	s_nop 0
	global_load_lds_dwordx4 v237, s[50:51]
	s_add_u32 m0, s99, 0x10000
	s_nop 0
	global_load_lds_dwordx4 v234, s[52:53]
	s_add_u32 m0, s99, 0x12000
	s_nop 0
	global_load_lds_dwordx4 v235, s[52:53]
	s_add_u32 m0, s99, 0x14000
	s_nop 0
	global_load_lds_dwordx4 v236, s[52:53]
	s_add_u32 m0, s99, 0x16000
	s_nop 0
	global_load_lds_dwordx4 v237, s[52:53]
.Ldma_skip_p:
	ds_read_b128 v[166:169], v191
	ds_read_b128 v[162:165], v0
	ds_read_b128 v[170:173], v191 offset:2048
	ds_read_b128 v[192:195], v191 offset:4096
	ds_read_b128 v[196:199], v191 offset:6144
	ds_read_b128 v[204:207], v0 offset:2048
	ds_read_b128 v[208:211], v0 offset:4096
	ds_read_b128 v[238:241], v0 offset:6144
	v_add_u32_e32 v191, v191, v190
; template <int MI, int NJ> ...
;     ...
;   for (int kt = 0; kt < nk; ++kt) {
;     const int buf = kt & 1;
;     {
;       G8STORE(buf ^ 1);
;       const u16* ga_ = (kt + 2 < nk) ? Ag + (kt + 2) * 64 : Ag + nAoff;
;       const u16* gb_ = (kt + 2 < nk) ? Bg + (kt + 2) * 64 : Bg + nBoff;
;       G8LOADP(ga_, gb_);
;     }
;     __builtin_amdgcn_sched_barrier(0);
;     __builtin_amdgcn_s_setprio(1);
;     const u16* a = ra_ + buf * AROWS * 64;
;     const u16* b = rb_ + buf * BROWS * 64;
; #pragma unroll
;     for (int ks = 0; ks < 2; ++ks) {
;       const u16* a_ = ks ? a + dsw : a;
;       const u16* b_ = ks ? b + dsw : b;
;       bf16x8 bfr[NJ];
; #pragma unroll
;       for (int j = 0; j < NJ; ++j) bfr[j] = *(const bf16x8*)(b_ + j * 16 * 64);
; #pragma unroll
;       for (int ih = 0; ih < MI / 4; ++ih) {
;         bf16x8 af[4];
; #pragma unroll
;         for (int i = 0; i < 4; ++i) af[i] = *(const bf16x8*)(a_ + (ih * 4 + i) * 16 * 64);
; #pragma unroll
;         for (int i = 0; i < 4; ++i)
; #pragma unroll
;           for (int j = 0; j < NJ; ++j) acc[ih * 4 + i][j] = mfma16(af[i], bfr[j], acc[ih * 4 + i][j]);
;       }
;     }
;     __builtin_amdgcn_s_setprio(0);
;     __builtin_amdgcn_sched_barrier(0);
;     __syncthreads();
.LBB0_481:
	s_setprio 1
	s_waitcnt lgkmcnt(6)
	v_mfma_f32_16x16x32_bf16 v[158:161], v[166:169], v[162:165], v[158:161]
	s_waitcnt lgkmcnt(5)
	v_mfma_f32_16x16x32_bf16 v[154:157], v[170:173], v[162:165], v[154:157]
	s_waitcnt lgkmcnt(4)
	v_mfma_f32_16x16x32_bf16 v[150:153], v[192:195], v[162:165], v[150:153]
	s_waitcnt lgkmcnt(3)
	v_mfma_f32_16x16x32_bf16 v[146:149], v[196:199], v[162:165], v[146:149]
	ds_read_b128 v[162:165], v0 offset:8192
	s_waitcnt lgkmcnt(3)
	v_mfma_f32_16x16x32_bf16 v[142:145], v[166:169], v[204:207], v[142:145]
	v_mfma_f32_16x16x32_bf16 v[138:141], v[170:173], v[204:207], v[138:141]
	v_mfma_f32_16x16x32_bf16 v[134:137], v[192:195], v[204:207], v[134:137]
	v_mfma_f32_16x16x32_bf16 v[130:133], v[196:199], v[204:207], v[130:133]
	ds_read_b128 v[204:207], v0 offset:10240
	s_waitcnt lgkmcnt(3)
	v_mfma_f32_16x16x32_bf16 v[126:129], v[166:169], v[208:211], v[126:129]
	v_mfma_f32_16x16x32_bf16 v[122:125], v[170:173], v[208:211], v[122:125]
	v_mfma_f32_16x16x32_bf16 v[118:121], v[192:195], v[208:211], v[118:121]
	v_mfma_f32_16x16x32_bf16 v[114:117], v[196:199], v[208:211], v[114:117]
	ds_read_b128 v[208:211], v0 offset:12288
	ds_read_b128 v[212:215], v191
	ds_read_b128 v[216:219], v191 offset:2048
	s_waitcnt lgkmcnt(5)
	v_mfma_f32_16x16x32_bf16 v[110:113], v[166:169], v[238:241], v[110:113]
	v_mfma_f32_16x16x32_bf16 v[106:109], v[170:173], v[238:241], v[106:109]
	v_mfma_f32_16x16x32_bf16 v[102:105], v[192:195], v[238:241], v[102:105]
	v_mfma_f32_16x16x32_bf16 v[98:101], v[196:199], v[238:241], v[98:101]
	ds_read_b128 v[238:241], v0 offset:14336
	ds_read_b128 v[220:223], v191 offset:4096
	ds_read_b128 v[224:227], v191 offset:6144
	s_waitcnt lgkmcnt(7)
	v_mfma_f32_16x16x32_bf16 v[94:97], v[166:169], v[162:165], v[94:97]
	v_mfma_f32_16x16x32_bf16 v[90:93], v[170:173], v[162:165], v[90:93]
	v_mfma_f32_16x16x32_bf16 v[86:89], v[192:195], v[162:165], v[86:89]
	v_mfma_f32_16x16x32_bf16 v[82:85], v[196:199], v[162:165], v[82:85]
	v_add_u32_e32 v0, v0, v190
	ds_read_b128 v[162:165], v0
	s_waitcnt lgkmcnt(7)
	v_mfma_f32_16x16x32_bf16 v[78:81], v[166:169], v[204:207], v[78:81]
	v_mfma_f32_16x16x32_bf16 v[70:73], v[170:173], v[204:207], v[70:73]
	v_mfma_f32_16x16x32_bf16 v[66:69], v[192:195], v[204:207], v[66:69]
	v_mfma_f32_16x16x32_bf16 v[58:61], v[196:199], v[204:207], v[58:61]
	ds_read_b128 v[204:207], v0 offset:2048
	s_waitcnt lgkmcnt(7)
	v_mfma_f32_16x16x32_bf16 v[54:57], v[166:169], v[208:211], v[54:57]
	v_mfma_f32_16x16x32_bf16 v[50:53], v[170:173], v[208:211], v[50:53]
	v_mfma_f32_16x16x32_bf16 v[46:49], v[192:195], v[208:211], v[46:49]
	v_mfma_f32_16x16x32_bf16 v[38:41], v[196:199], v[208:211], v[38:41]
	ds_read_b128 v[208:211], v0 offset:4096
	s_waitcnt lgkmcnt(5)
	v_mfma_f32_16x16x32_bf16 v[34:37], v[166:169], v[238:241], v[34:37]
	v_mfma_f32_16x16x32_bf16 v[30:33], v[170:173], v[238:241], v[30:33]
	v_mfma_f32_16x16x32_bf16 v[26:29], v[192:195], v[238:241], v[26:29]
	v_mfma_f32_16x16x32_bf16 v[22:25], v[196:199], v[238:241], v[22:25]
	ds_read_b128 v[238:241], v0 offset:6144
	s_waitcnt lgkmcnt(3)
	v_mfma_f32_16x16x32_bf16 v[158:161], v[212:215], v[162:165], v[158:161]
	v_mfma_f32_16x16x32_bf16 v[154:157], v[216:219], v[162:165], v[154:157]
	v_mfma_f32_16x16x32_bf16 v[150:153], v[220:223], v[162:165], v[150:153]
	v_mfma_f32_16x16x32_bf16 v[146:149], v[224:227], v[162:165], v[146:149]
	ds_read_b128 v[162:165], v0 offset:8192
	s_waitcnt lgkmcnt(3)
	v_mfma_f32_16x16x32_bf16 v[142:145], v[212:215], v[204:207], v[142:145]
	v_mfma_f32_16x16x32_bf16 v[138:141], v[216:219], v[204:207], v[138:141]
	v_mfma_f32_16x16x32_bf16 v[134:137], v[220:223], v[204:207], v[134:137]
	v_mfma_f32_16x16x32_bf16 v[130:133], v[224:227], v[204:207], v[130:133]
	ds_read_b128 v[204:207], v0 offset:10240
	s_waitcnt lgkmcnt(3)
	v_mfma_f32_16x16x32_bf16 v[126:129], v[212:215], v[208:211], v[126:129]
	v_mfma_f32_16x16x32_bf16 v[122:125], v[216:219], v[208:211], v[122:125]
	v_mfma_f32_16x16x32_bf16 v[118:121], v[220:223], v[208:211], v[118:121]
	v_mfma_f32_16x16x32_bf16 v[114:117], v[224:227], v[208:211], v[114:117]
	ds_read_b128 v[208:211], v0 offset:12288
	s_waitcnt lgkmcnt(3)
	v_mfma_f32_16x16x32_bf16 v[110:113], v[212:215], v[238:241], v[110:113]
	v_mfma_f32_16x16x32_bf16 v[106:109], v[216:219], v[238:241], v[106:109]
	v_mfma_f32_16x16x32_bf16 v[102:105], v[220:223], v[238:241], v[102:105]
	v_mfma_f32_16x16x32_bf16 v[98:101], v[224:227], v[238:241], v[98:101]
	ds_read_b128 v[238:241], v0 offset:14336
	s_waitcnt lgkmcnt(3)
	v_mfma_f32_16x16x32_bf16 v[94:97], v[212:215], v[162:165], v[94:97]
	v_mfma_f32_16x16x32_bf16 v[90:93], v[216:219], v[162:165], v[90:93]
	v_mfma_f32_16x16x32_bf16 v[86:89], v[220:223], v[162:165], v[86:89]
	v_mfma_f32_16x16x32_bf16 v[82:85], v[224:227], v[162:165], v[82:85]
	s_waitcnt vmcnt(0)
	s_waitcnt lgkmcnt(0)
	s_setprio 0
	s_barrier
	s_add_i32 s44, s44, 1
	s_add_i32 s39, s39, 64
	s_addk_i32 s43, 0x4000
	s_and_b32 s45, s43, 0x4000
	s_sub_i32 s67, s39, 64
	s_add_i32 s46, s44, 1
	s_cmp_lt_u32 s46, s21
	s_cselect_b32 s47, 0, s12
	s_cselect_b32 s46, s67, s13
	s_cselect_b32 s49, 0, s37
	s_cselect_b32 s48, s67, s38
	s_lshl_b64 s[46:47], s[46:47], 1
	s_lshl_b64 s[48:49], s[48:49], 1
	s_add_u32 s50, s62, s46
	s_addc_u32 s51, s63, s47
	s_add_u32 s52, s64, s48
	s_addc_u32 s53, s65, s49
	s_lshl_b32 s45, s45, 1
	v_add_u32_e32 v0, s45, v187
	v_add_u32_e32 v191, s45, v188
	s_add_i32 s98, s44, 1
	s_cmp_lt_u32 s98, s21
	s_cbranch_scc0 .Ldma_skip_l
	s_and_b32 s99, s44, 1
	s_xor_b32 s99, s99, 1
	s_lshl_b32 s99, s99, 15
	s_add_u32 s99, s99, s66
	s_mov_b32 m0, s99
	s_nop 0
	global_load_lds_dwordx4 v234, s[50:51]
	s_add_u32 m0, s99, 0x2000
	s_nop 0
	global_load_lds_dwordx4 v235, s[50:51]
	s_add_u32 m0, s99, 0x4000
	s_nop 0
	global_load_lds_dwordx4 v236, s[50:51]
	s_add_u32 m0, s99, 0x6000
	s_nop 0
	global_load_lds_dwordx4 v237, s[50:51]
	s_add_u32 m0, s99, 0x10000
	s_nop 0
	global_load_lds_dwordx4 v234, s[52:53]
	s_add_u32 m0, s99, 0x12000
	s_nop 0
	global_load_lds_dwordx4 v235, s[52:53]
	s_add_u32 m0, s99, 0x14000
	s_nop 0
	global_load_lds_dwordx4 v236, s[52:53]
	s_add_u32 m0, s99, 0x16000
	s_nop 0
	global_load_lds_dwordx4 v237, s[52:53]
; template <int MI, int NJ> ...
;     ...
;   for (int kt = 0; kt < nk; ++kt) {
;     const int buf = kt & 1;
;     {
;       G8STORE(buf ^ 1);
;       const u16* ga_ = (kt + 2 < nk) ? Ag + (kt + 2) * 64 : Ag + nAoff;
;       const u16* gb_ = (kt + 2 < nk) ? Bg + (kt + 2) * 64 : Bg + nBoff;
;       G8LOADP(ga_, gb_);
;     }
;     __builtin_amdgcn_sched_barrier(0);
;     __builtin_amdgcn_s_setprio(1);
;     const u16* a = ra_ + buf * AROWS * 64;
;     const u16* b = rb_ + buf * BROWS * 64;
; #pragma unroll
;     for (int ks = 0; ks < 2; ++ks) {
;       const u16* a_ = ks ? a + dsw : a;
;       const u16* b_ = ks ? b + dsw : b;
;       bf16x8 bfr[NJ];
; #pragma unroll
;       for (int j = 0; j < NJ; ++j) bfr[j] = *(const bf16x8*)(b_ + j * 16 * 64);
; #pragma unroll
;       for (int ih = 0; ih < MI / 4; ++ih) {
;         bf16x8 af[4];
; #pragma unroll
;         for (int i = 0; i < 4; ++i) af[i] = *(const bf16x8*)(a_ + (ih * 4 + i) * 16 * 64);
; #pragma unroll
;         for (int i = 0; i < 4; ++i)
; #pragma unroll
;           for (int j = 0; j < NJ; ++j) acc[ih * 4 + i][j] = mfma16(af[i], bfr[j], acc[ih * 4 + i][j]);
;       }
;     }
;     __builtin_amdgcn_s_setprio(0);
;     __builtin_amdgcn_sched_barrier(0);
;     __syncthreads();
; __device__ __forceinline__ void phase_gemm_f32(const u16* A, const u16* Bt, int K, u16* out, u16* smem,
;                                                volatile LAS unsigned* vb_) {
;     ...
; #pragma unroll
;     for (int i = 0; i < 8; ++i)
; #pragma unroll
;       for (int j = 0; j < 4; ++j)
; #pragma unroll
;         for (int r = 0; r < 4; ++r)
;           smem[(wm * 128 + i * 16 + (lane >> 4) * 4 + r) * 264 + wn * 64 + j * 16 + (lane & 15)] = f2bf(acc[i][j][r]);
;     __syncthreads();
.Ldma_skip_l:
	s_setprio 1
	ds_read_b128 v[166:169], v191
	ds_read_b128 v[162:165], v0
	ds_read_b128 v[170:173], v191 offset:2048
	ds_read_b128 v[192:195], v191 offset:4096
	ds_read_b128 v[196:199], v191 offset:6144
	v_mfma_f32_16x16x32_bf16 v[78:81], v[212:215], v[204:207], v[78:81]
	v_mfma_f32_16x16x32_bf16 v[70:73], v[216:219], v[204:207], v[70:73]
	v_mfma_f32_16x16x32_bf16 v[66:69], v[220:223], v[204:207], v[66:69]
	v_mfma_f32_16x16x32_bf16 v[58:61], v[224:227], v[204:207], v[58:61]
	ds_read_b128 v[204:207], v0 offset:2048
	v_mfma_f32_16x16x32_bf16 v[54:57], v[212:215], v[208:211], v[54:57]
	v_mfma_f32_16x16x32_bf16 v[50:53], v[216:219], v[208:211], v[50:53]
	v_mfma_f32_16x16x32_bf16 v[46:49], v[220:223], v[208:211], v[46:49]
	v_mfma_f32_16x16x32_bf16 v[38:41], v[224:227], v[208:211], v[38:41]
	ds_read_b128 v[208:211], v0 offset:4096
	v_mfma_f32_16x16x32_bf16 v[34:37], v[212:215], v[238:241], v[34:37]
	v_mfma_f32_16x16x32_bf16 v[30:33], v[216:219], v[238:241], v[30:33]
	v_mfma_f32_16x16x32_bf16 v[26:29], v[220:223], v[238:241], v[26:29]
	v_mfma_f32_16x16x32_bf16 v[22:25], v[224:227], v[238:241], v[22:25]
	ds_read_b128 v[238:241], v0 offset:6144
	v_add_u32_e32 v191, v191, v190
	s_setprio 0
	s_cmp_lg_u32 s21, s44
	s_cbranch_scc1 .LBB0_481
	v_and_b32_e32 v228, 15, v175
	v_bfe_u32 v229, v175, 8, 1
	v_lshl_or_b32 v228, v229, 7, v228
	v_mul_u32_u24_e32 v228, 0x210, v228
	v_bfe_u32 v229, v175, 6, 2
	v_lshl_add_u32 v228, v229, 7, v228
	v_bfe_u32 v229, v175, 4, 2
	v_lshl_add_u32 v228, v229, 3, v228
	v_cvt_pk_bf16_f32 v158, v158, v159
	v_cvt_pk_bf16_f32 v159, v160, v161
	v_cvt_pk_bf16_f32 v154, v154, v155
	v_cvt_pk_bf16_f32 v155, v156, v157
	v_cvt_pk_bf16_f32 v150, v150, v151
	v_cvt_pk_bf16_f32 v151, v152, v153
	v_cvt_pk_bf16_f32 v146, v146, v147
	v_cvt_pk_bf16_f32 v147, v148, v149
	ds_write_b64 v228, v[158:159]
	ds_write_b64 v228, v[154:155] offset:32
	ds_write_b64 v228, v[150:151] offset:64
	ds_write_b64 v228, v[146:147] offset:96
	v_cvt_pk_bf16_f32 v142, v142, v143
	v_cvt_pk_bf16_f32 v143, v144, v145
	v_cvt_pk_bf16_f32 v138, v138, v139
	v_cvt_pk_bf16_f32 v139, v140, v141
	v_cvt_pk_bf16_f32 v134, v134, v135
	v_cvt_pk_bf16_f32 v135, v136, v137
	v_cvt_pk_bf16_f32 v130, v130, v131
	v_cvt_pk_bf16_f32 v131, v132, v133
	ds_write_b64 v228, v[142:143] offset:8448
	ds_write_b64 v228, v[138:139] offset:8480
	ds_write_b64 v228, v[134:135] offset:8512
	ds_write_b64 v228, v[130:131] offset:8544
	v_cvt_pk_bf16_f32 v126, v126, v127
	v_cvt_pk_bf16_f32 v127, v128, v129
	v_cvt_pk_bf16_f32 v122, v122, v123
	v_cvt_pk_bf16_f32 v123, v124, v125
	v_cvt_pk_bf16_f32 v118, v118, v119
	v_cvt_pk_bf16_f32 v119, v120, v121
	v_cvt_pk_bf16_f32 v114, v114, v115
	v_cvt_pk_bf16_f32 v115, v116, v117
	ds_write_b64 v228, v[126:127] offset:16896
	ds_write_b64 v228, v[122:123] offset:16928
	ds_write_b64 v228, v[118:119] offset:16960
	ds_write_b64 v228, v[114:115] offset:16992
	v_cvt_pk_bf16_f32 v110, v110, v111
	v_cvt_pk_bf16_f32 v111, v112, v113
	v_cvt_pk_bf16_f32 v106, v106, v107
	v_cvt_pk_bf16_f32 v107, v108, v109
	v_cvt_pk_bf16_f32 v102, v102, v103
	v_cvt_pk_bf16_f32 v103, v104, v105
	v_cvt_pk_bf16_f32 v98, v98, v99
	v_cvt_pk_bf16_f32 v99, v100, v101
	ds_write_b64 v228, v[110:111] offset:25344
	ds_write_b64 v228, v[106:107] offset:25376
	ds_write_b64 v228, v[102:103] offset:25408
	ds_write_b64 v228, v[98:99] offset:25440
	v_cvt_pk_bf16_f32 v94, v94, v95
	v_cvt_pk_bf16_f32 v95, v96, v97
	v_cvt_pk_bf16_f32 v90, v90, v91
	v_cvt_pk_bf16_f32 v91, v92, v93
	v_cvt_pk_bf16_f32 v86, v86, v87
	v_cvt_pk_bf16_f32 v87, v88, v89
	v_cvt_pk_bf16_f32 v82, v82, v83
	v_cvt_pk_bf16_f32 v83, v84, v85
	ds_write_b64 v228, v[94:95] offset:33792
	ds_write_b64 v228, v[90:91] offset:33824
	ds_write_b64 v228, v[86:87] offset:33856
	ds_write_b64 v228, v[82:83] offset:33888
	v_cvt_pk_bf16_f32 v78, v78, v79
	v_cvt_pk_bf16_f32 v79, v80, v81
	v_cvt_pk_bf16_f32 v70, v70, v71
	v_cvt_pk_bf16_f32 v71, v72, v73
	v_cvt_pk_bf16_f32 v66, v66, v67
	v_cvt_pk_bf16_f32 v67, v68, v69
	v_cvt_pk_bf16_f32 v58, v58, v59
	v_cvt_pk_bf16_f32 v59, v60, v61
	ds_write_b64 v228, v[78:79] offset:42240
	ds_write_b64 v228, v[70:71] offset:42272
	ds_write_b64 v228, v[66:67] offset:42304
	ds_write_b64 v228, v[58:59] offset:42336
	v_cvt_pk_bf16_f32 v54, v54, v55
	v_cvt_pk_bf16_f32 v55, v56, v57
	v_cvt_pk_bf16_f32 v50, v50, v51
	v_cvt_pk_bf16_f32 v51, v52, v53
	v_cvt_pk_bf16_f32 v46, v46, v47
	v_cvt_pk_bf16_f32 v47, v48, v49
	v_cvt_pk_bf16_f32 v38, v38, v39
	v_cvt_pk_bf16_f32 v39, v40, v41
	ds_write_b64 v228, v[54:55] offset:50688
	ds_write_b64 v228, v[50:51] offset:50720
	ds_write_b64 v228, v[46:47] offset:50752
	ds_write_b64 v228, v[38:39] offset:50784
	v_cvt_pk_bf16_f32 v34, v34, v35
	v_cvt_pk_bf16_f32 v35, v36, v37
	v_cvt_pk_bf16_f32 v30, v30, v31
	v_cvt_pk_bf16_f32 v31, v32, v33
	v_cvt_pk_bf16_f32 v26, v26, v27
	v_cvt_pk_bf16_f32 v27, v28, v29
	v_cvt_pk_bf16_f32 v22, v22, v23
	v_cvt_pk_bf16_f32 v23, v24, v25
	ds_write_b64 v228, v[34:35] offset:59136
	ds_write_b64 v228, v[30:31] offset:59168
	ds_write_b64 v228, v[26:27] offset:59200
	ds_write_b64 v228, v[22:23] offset:59232
	s_ashr_i32 s43, s42, 31
	v_mov_b32_e32 v34, v175
	s_lshl_b64 s[12:13], s[42:43], 1
	s_waitcnt lgkmcnt(0)
	s_barrier
; #define RTID opaque_tid()
; __device__ __forceinline__ void phase_gemm_f32(const u16* A, const u16* Bt, int K, u16* out, u16* smem,
;                                                volatile LAS unsigned* vb_) {
;     ...
;     const int tid2 = RTID;
; #pragma unroll
;     for (int k = 0; k < 16; ++k) {
;       const int c = tid2 + 512 * k;
;       const int row = c >> 5, ch = c & 31;
;       const uint4 v = *(const uint4*)(smem + row * 264 + ch * 8);
;       *(uint4*)(out + (size_t)(mt * 256 + row) * 1024 + nt * 256 + ch * 8) = v;
;     }
;     __syncthreads();
	s_add_u32 s12, s11, s12
	s_addc_u32 s13, s20, s13
	v_lshlrev_b32_e32 v0, 4, v34
	v_and_b32_e32 v0, 0x1f0, v0
	v_ashrrev_i32_e32 v26, 5, v34
	v_mad_u32_u24 v22, v26, s2, v0
	v_add_u32_e32 v23, 0x10800, v22
	ds_read_b128 v[98:101], v22
	ds_read_b128 v[102:105], v22 offset:8448
	ds_read_b128 v[106:109], v22 offset:16896
	ds_read_b128 v[110:113], v22 offset:25344
	ds_read_b128 v[114:117], v22 offset:33792
	ds_read_b128 v[118:121], v22 offset:42240
	ds_read_b128 v[122:125], v22 offset:50688
	ds_read_b128 v[126:129], v22 offset:59136
	v_add_u32_e32 v26, s23, v26
	v_ashrrev_i32_e32 v27, 31, v26
	v_lshlrev_b64 v[26:27], 11, v[26:27]
	v_lshl_add_u64 v[32:33], s[12:13], 0, v[26:27]
	v_lshl_add_u64 v[32:33], v[32:33], 0, v[0:1]
	s_mov_b32 s48, 0x8000
	s_mov_b32 s49, 0
	s_and_b64 vcc, exec, s[40:41]
	s_mov_b32 s37, s36
	s_waitcnt lgkmcnt(7)
	global_store_dwordx4 v[32:33], v[98:101], off
	s_nop 0
	ds_read_b128 v[98:101], v23
	v_lshl_add_u64 v[32:33], v[32:33], 0, s[48:49]
	s_waitcnt lgkmcnt(7)
	global_store_dwordx4 v[32:33], v[102:105], off
	s_nop 0
	ds_read_b128 v[102:105], v23 offset:8448
	v_lshl_add_u64 v[32:33], v[32:33], 0, s[48:49]
	s_waitcnt lgkmcnt(7)
	global_store_dwordx4 v[32:33], v[106:109], off
	s_nop 0
	ds_read_b128 v[106:109], v23 offset:16896
	v_lshl_add_u64 v[32:33], v[32:33], 0, s[48:49]
	s_waitcnt lgkmcnt(7)
	global_store_dwordx4 v[32:33], v[110:113], off
	s_nop 0
	ds_read_b128 v[110:113], v23 offset:25344
	v_lshl_add_u64 v[32:33], v[32:33], 0, s[48:49]
	s_waitcnt lgkmcnt(7)
	global_store_dwordx4 v[32:33], v[114:117], off
	s_nop 0
	ds_read_b128 v[114:117], v23 offset:33792
	v_lshl_add_u64 v[32:33], v[32:33], 0, s[48:49]
	s_waitcnt lgkmcnt(7)
	global_store_dwordx4 v[32:33], v[118:121], off
	s_nop 0
	ds_read_b128 v[118:121], v23 offset:42240
	v_lshl_add_u64 v[32:33], v[32:33], 0, s[48:49]
	s_waitcnt lgkmcnt(7)
	global_store_dwordx4 v[32:33], v[122:125], off
	s_nop 0
	ds_read_b128 v[122:125], v23 offset:50688
	v_lshl_add_u64 v[32:33], v[32:33], 0, s[48:49]
	s_waitcnt lgkmcnt(7)
	global_store_dwordx4 v[32:33], v[126:129], off
	s_nop 0
	ds_read_b128 v[126:129], v23 offset:59136
	v_lshl_add_u64 v[32:33], v[32:33], 0, s[48:49]
	s_waitcnt lgkmcnt(7)
	global_store_dwordx4 v[32:33], v[98:101], off
	v_lshl_add_u64 v[32:33], v[32:33], 0, s[48:49]
	s_waitcnt lgkmcnt(6)
	global_store_dwordx4 v[32:33], v[102:105], off
	v_lshl_add_u64 v[32:33], v[32:33], 0, s[48:49]
	s_waitcnt lgkmcnt(5)
	global_store_dwordx4 v[32:33], v[106:109], off
	v_lshl_add_u64 v[32:33], v[32:33], 0, s[48:49]
	s_waitcnt lgkmcnt(4)
	global_store_dwordx4 v[32:33], v[110:113], off
	v_lshl_add_u64 v[32:33], v[32:33], 0, s[48:49]
	s_waitcnt lgkmcnt(3)
	global_store_dwordx4 v[32:33], v[114:117], off
	v_lshl_add_u64 v[32:33], v[32:33], 0, s[48:49]
	s_waitcnt lgkmcnt(2)
	global_store_dwordx4 v[32:33], v[118:121], off
	v_lshl_add_u64 v[32:33], v[32:33], 0, s[48:49]
	s_waitcnt lgkmcnt(1)
	global_store_dwordx4 v[32:33], v[122:125], off
	v_lshl_add_u64 v[32:33], v[32:33], 0, s[48:49]
	s_waitcnt lgkmcnt(0)
	global_store_dwordx4 v[32:33], v[126:129], off
	s_mov_b64 s[12:13], -1
	s_barrier
	s_cbranch_vccz .LBB0_478
